# P7 up projection: workgroups start staggered by (blockIdx&7) x ~1.5us (same idea as P2)
# speedup vs baseline: 1.0022x; 1.0022x over previous
;     __device__ void init(int G_, int c_) { so.init(16384, 12288, G_, c_); G = G_; c = c_; }
;     __device__ bool next(int i, Unit& o) const { if (i != 0) return false; o = u; return true; }
; __global__ void __launch_bounds__(512, 2) fwd_megakernel(Params p_unused) {
;     ...
;     pg8::StaticOrder so; so.init(MTOK, FF2, G, bx);
;     pg8::Gemm g{H2, WUP, MTOK, FF2, DM, DM}; pg8::EpiConv E{U, SIDE, p.conv_w, p.conv_b};
;     pg8::Unit uu;
;     for (int i = 0; so.next(i, uu); ++i) { pg8::OneUnit S1{uu}; pg8::gemm_phase<pg8::EpiConv, pg8::OneUnit, false, true>(glds, g, S1, E); }
.LBB0_727:
	s_or_b64 exec, exec, s[4:5]
	s_mov_b64 s[0:1], s[86:87]
	s_waitcnt lgkmcnt(0)
	s_barrier
	s_and_b32 s98, s96, 7
	s_cbranch_scc0 .Lskew_p7_done
.Lskew_p7_loop:
	s_sleep 48
	s_add_i32 s98, s98, -1
	s_cmp_lg_u32 s98, 0
	s_cbranch_scc1 .Lskew_p7_loop
.Lskew_p7_done:
	s_load_dwordx2 s[6:7], s[0:1], 0xc8
	s_load_dwordx4 s[8:11], s[0:1], 0xa0
	v_mov_b32_e32 v0, v194
	s_mov_b32 s18, 0
	v_mov_b64_e32 v[128:129], 0xb00
	s_waitcnt lgkmcnt(0)
	s_add_u32 s1, s6, 0x5b00000
	s_addc_u32 s38, s7, 0
	s_add_u32 s39, s6, 0x200000
	s_addc_u32 s40, s7, 0
	s_add_u32 s16, s6, 0x9b00000
	s_addc_u32 s17, s7, 0
	s_add_u32 s41, s6, 0x4400000
	s_addc_u32 s42, s7, 0
	s_add_u32 s43, s6, 0x5b80080
	s_addc_u32 s44, s7, 0
	s_add_u32 s45, s6, 0x200100
	s_addc_u32 s46, s7, 0
	v_mov_b64_e32 v[130:131], 0xaff
	s_movk_i32 s47, 0x161
	s_mov_b32 s48, 0xfffe0
	v_mov_b32_e32 v133, 0
	s_mov_b32 s49, 0x16000
	s_mov_b64 s[20:21], 0x80
	s_mov_b64 s[22:23], 0xb000
	s_mov_b64 s[24:25], 0x16000
	s_mov_b32 s50, 0xb000
	s_movk_i32 s51, 0xffc0
	s_movk_i32 s52, 0x101
	s_movk_i32 s53, 0x100
	s_movk_i32 s54, 0x2c00
	s_movk_i32 s55, 0x80
	v_mov_b32_e32 v144, 1
	s_mov_b32 s60, 0
	s_branch .LBB0_730
